# combo4 = combo2 + waves whose 32 list slots are all padding skip the attention tile in the selected-block phase
# speedup vs baseline: 1.0027x; 1.0027x over previous
; __global__ void __launch_bounds__(512, 2) mk_fwd(Args a) {
;     ...
;                 for (int it = vcu; it < total; it += G) {
;                     TID_LOCALS
;                     int lo = 0, hh = 511;
;                     while (lo < hh) { const int mid = (lo + hh) >> 1; if (pre[mid] > it) hh = mid; else lo = mid + 1; }
;                     const int p = lo, chunk = it - (p ? pre[p - 1] : 0), h = p >> 6, b = p & 63;
;                     const int pc = (int)CNT[l * 512 + p];
;                     const int e = chunk * 256 + 32 * wave + r32; const bool valid = e < pc;
;                     const unsigned ent = LIST[(size_t)p * SEQ + (valid ? e : 0)];
;                     u32x4 kr[8], vr[8];
;                     stage_kv_load(kr, vr, PROJ + (size_t)(256 * b) * INW + 1024 + 128 * h, INW, VT + (size_t)(h * 64 + b) * 128 * 256, tid);
.LBB0_51:
	s_ashr_i32 s7, s6, 31
	s_lshr_b32 s28, s6, 6
	s_and_b32 s18, s6, 63
	s_lshl_b64 s[16:17], s[6:7], 2
	v_mov_b32_e32 v2, s16
	v_add_u32_e32 v2, 0x23000, v2
	ds_read_b32 v12, v2
	s_mov_b32 s7, s75
	s_ashr_i32 s15, s15, 1
	s_lshl_b64 s[6:7], s[6:7], 16
	s_andn2_b32 s15, s15, 31
	s_waitcnt lgkmcnt(0)
	v_sub_u32_e32 v1, s14, v1
	s_add_u32 s16, s58, s6
	v_lshlrev_b32_e32 v1, 8, v1
	s_mul_i32 s18, s18, 0x280000
	s_addc_u32 s17, s59, s7
	v_add_u32_e32 v1, s15, v1
	s_add_u32 s15, s72, s18
	s_addc_u32 s19, s73, 0
	s_lshl_b32 s74, s28, 8
	v_lshlrev_b32_e32 v2, 4, v0
	s_add_u32 s18, s15, s74
	v_mov_b32_e32 v67, v129
	v_add_u32_e32 v3, 0x200, v0
	v_add_u32_e32 v4, 0x400, v0
	v_add_u32_e32 v6, 0x800, v0
	v_add_u32_e32 v7, 0xa00, v0
	v_and_b32_e32 v66, 0xf0, v2
	s_addc_u32 s19, s19, 0
	v_and_b32_e32 v163, 31, v0
	v_ashrrev_i32_e32 v88, 4, v0
	v_add_u32_e32 v8, 0xc00, v0
	v_add_u32_e32 v9, 0xe00, v0
	v_ashrrev_i32_e32 v90, 4, v3
	v_ashrrev_i32_e32 v92, 4, v4
	v_ashrrev_i32_e32 v96, 4, v6
	v_ashrrev_i32_e32 v98, 4, v7
	v_ashrrev_i32_e32 v78, 5, v6
	v_ashrrev_i32_e32 v80, 5, v7
	s_add_u32 s22, s96, s6
	v_lshl_add_u64 v[6:7], s[18:19], 0, v[66:67]
	s_movk_i32 s18, 0x2800
	v_ashrrev_i32_e32 v100, 4, v8
	v_ashrrev_i32_e32 v102, 4, v9
	v_and_b32_e32 v68, 0x1f0, v2
	v_ashrrev_i32_e32 v72, 5, v3
	v_ashrrev_i32_e32 v82, 5, v8
	v_ashrrev_i32_e32 v84, 5, v9
	v_or_b32_e32 v1, v1, v163
	s_addc_u32 s23, s97, s7
	v_mad_i64_i32 v[2:3], s[6:7], v88, s18, v[6:7]
	v_mad_i64_i32 v[8:9], s[6:7], v90, s18, v[6:7]
	v_mad_i64_i32 v[10:11], s[6:7], v92, s18, v[6:7]
	v_add_u32_e32 v5, 0x600, v0
	v_ashrrev_i32_e32 v70, 5, v0
	v_ashrrev_i32_e32 v74, 5, v4
	v_ashrrev_i32_e32 v76, 5, v5
	v_bfe_u32 v167, v0, 5, 1
	v_mov_b32_e32 v69, v129
	v_ashrrev_i32_e32 v71, 31, v70
	v_ashrrev_i32_e32 v73, 31, v72
	v_ashrrev_i32_e32 v75, 31, v74
	v_ashrrev_i32_e32 v77, 31, v76
	v_ashrrev_i32_e32 v79, 31, v78
	v_ashrrev_i32_e32 v81, 31, v80
	v_ashrrev_i32_e32 v83, 31, v82
	v_ashrrev_i32_e32 v85, 31, v84
	v_ashrrev_i32_e32 v94, 4, v5
	v_lshlrev_b64 v[34:35], 9, v[70:71]
	v_lshlrev_b64 v[36:37], 9, v[72:73]
	v_lshlrev_b64 v[38:39], 9, v[74:75]
	v_lshl_add_u64 v[62:63], s[22:23], 0, v[68:69]
	v_lshlrev_b64 v[46:47], 9, v[76:77]
	v_lshlrev_b64 v[50:51], 9, v[78:79]
	v_lshlrev_b64 v[54:55], 9, v[80:81]
	v_lshlrev_b64 v[58:59], 9, v[82:83]
	v_lshlrev_b64 v[64:65], 9, v[84:85]
	v_mov_b32_e32 v87, v129
	v_lshlrev_b32_e32 v86, 4, v167
	v_lshl_add_u64 v[34:35], v[62:63], 0, v[34:35]
	v_lshl_add_u64 v[40:41], v[62:63], 0, v[36:37]
	v_lshl_add_u64 v[42:43], v[62:63], 0, v[38:39]
	v_lshl_add_u64 v[46:47], v[62:63], 0, v[46:47]
	v_cmp_lt_i32_e64 s[6:7], v1, v12
	v_lshl_add_u64 v[50:51], v[62:63], 0, v[50:51]
	v_lshl_add_u64 v[54:55], v[62:63], 0, v[54:55]
	v_cndmask_b32_e64 v12, 0, v1, s[6:7]
	v_ashrrev_i32_e32 v13, 31, v12
	v_lshl_add_u64 v[12:13], v[12:13], 2, s[16:17]
	global_load_dword v168, v[12:13], off
	v_mov_b64_e32 v[0:1], s[72:73]
	v_mad_i64_i32 v[14:15], s[16:17], v94, s18, v[6:7]
	v_mad_i64_i32 v[18:19], s[16:17], v96, s18, v[6:7]
	v_mad_i64_i32 v[22:23], s[16:17], v98, s18, v[6:7]
	v_mad_i64_i32 v[26:27], s[16:17], v100, s18, v[6:7]
	v_mad_i64_i32 v[30:31], s[16:17], v102, s18, v[6:7]
	v_lshl_add_u64 v[58:59], v[62:63], 0, v[58:59]
	v_lshl_add_u64 v[62:63], v[62:63], 0, v[64:65]
	global_load_dwordx4 v[2:5], v[2:3], off offset:2048
	s_nop 0
	global_load_dwordx4 v[6:9], v[8:9], off offset:2048
	s_nop 0
	global_load_dwordx4 v[10:13], v[10:11], off offset:2048
	s_nop 0
	global_load_dwordx4 v[14:17], v[14:15], off offset:2048
	s_nop 0
	global_load_dwordx4 v[18:21], v[18:19], off offset:2048
	s_nop 0
	global_load_dwordx4 v[22:25], v[22:23], off offset:2048
	s_nop 0
	global_load_dwordx4 v[26:29], v[26:27], off offset:2048
	s_nop 0
	global_load_dwordx4 v[30:33], v[30:31], off offset:2048
	s_nop 0
	global_load_dwordx4 v[34:37], v[34:35], off
	s_nop 0
	global_load_dwordx4 v[38:41], v[40:41], off
	s_nop 0
	global_load_dwordx4 v[42:45], v[42:43], off
	v_readlane_b32 s19, v254, 28
	global_load_dwordx4 v[46:49], v[46:47], off
	v_add_u32_e32 v66, 0, v66
	global_load_dwordx4 v[50:53], v[50:51], off
	v_add_u32_e32 v68, s19, v68
	global_load_dwordx4 v[54:57], v[54:55], off
	s_movk_i32 s20, 0x210
	global_load_dwordx4 v[58:61], v[58:59], off
	v_mad_u64_u32 v[88:89], s[16:17], v88, s86, v[66:67]
	global_load_dwordx4 v[62:65], v[62:63], off
	v_mad_u64_u32 v[90:91], s[16:17], v90, s86, v[66:67]
	v_mad_u64_u32 v[92:93], s[16:17], v92, s86, v[66:67]
	v_mad_u64_u32 v[94:95], s[16:17], v94, s86, v[66:67]
	v_mad_u64_u32 v[96:97], s[16:17], v96, s86, v[66:67]
	v_mad_u64_u32 v[98:99], s[16:17], v98, s86, v[66:67]
	v_mad_u64_u32 v[100:101], s[16:17], v100, s86, v[66:67]
	v_mad_u64_u32 v[66:67], s[16:17], v102, s86, v[66:67]
	v_mad_u64_u32 v[70:71], s[16:17], v70, s20, v[68:69]
	v_mad_u64_u32 v[72:73], s[16:17], v72, s20, v[68:69]
	v_mad_u64_u32 v[74:75], s[16:17], v74, s20, v[68:69]
	v_lshlrev_b32_e32 v164, 3, v167
	s_mov_b32 s15, 0
	v_add_u32_e32 v169, 0, v86
	s_mov_b64 s[60:61], -1
	v_mov_b32_e32 v162, 0xf149f2ca
	s_waitcnt vmcnt(16)
; __global__ void __launch_bounds__(512, 2) mk_fwd(Args a) {
;     ...
;                     const int tok = (int)(ent >> 2), slot = (int)(ent & 3u);
;                     const bf16_t* qrow = PROJ + (size_t)tok * INW + 128 * h + 8 * hi;
;                     bf16x8 qf[8];
; #pragma unroll
;                     for (int d0 = 0; d0 < 8; ++d0) qf[d0] = *(const bf16x8*)(qrow + 16 * d0);
;                     stage_kv_store(lds, kr, vr, tid);
;                     __syncthreads();
;                     f32x16 O[4]; float m2, ll;
;                     attn_tile<false>(lds + LDS_KS, lds + LDS_VT, qf, 0, r32, hi, O, m2, ll);
	v_lshrrev_b32_e32 v128, 2, v168
	v_mad_u64_u32 v[0:1], s[16:17], v128, s18, v[0:1]
	v_lshl_add_u64 v[0:1], v[0:1], 0, s[74:75]
	v_lshl_add_u64 v[0:1], v[0:1], 0, v[86:87]
	global_load_dwordx4 v[130:133], v[0:1], off
	global_load_dwordx4 v[134:137], v[0:1], off offset:32
	global_load_dwordx4 v[138:141], v[0:1], off offset:64
	global_load_dwordx4 v[142:145], v[0:1], off offset:96
	global_load_dwordx4 v[146:149], v[0:1], off offset:128
	global_load_dwordx4 v[150:153], v[0:1], off offset:160
	global_load_dwordx4 v[154:157], v[0:1], off offset:192
	global_load_dwordx4 v[158:161], v[0:1], off offset:224
	v_mad_u64_u32 v[0:1], s[16:17], v76, s20, v[68:69]
	s_waitcnt vmcnt(8) lgkmcnt(0)
	ds_write_b128 v88, v[2:5]
	ds_write_b128 v90, v[6:9]
	ds_write_b128 v92, v[10:13]
	ds_write_b128 v94, v[14:17]
	ds_write_b128 v96, v[18:21]
	ds_write_b128 v98, v[22:25]
	ds_write_b128 v100, v[26:29]
	ds_write_b128 v66, v[30:33]
	ds_write_b128 v70, v[34:37]
	ds_write_b128 v72, v[38:41]
	ds_write_b128 v74, v[42:45]
	v_mov_b32_e32 v32, 0
	ds_write_b128 v0, v[46:49]
	v_mad_u64_u32 v[0:1], s[16:17], v78, s20, v[68:69]
	ds_write_b128 v0, v[50:53]
	v_mad_u64_u32 v[0:1], s[16:17], v80, s20, v[68:69]
	ds_write_b128 v0, v[54:57]
	v_mad_u64_u32 v[0:1], s[16:17], v82, s20, v[68:69]
	ds_write_b128 v0, v[58:61]
	v_mad_u64_u32 v[0:1], s[16:17], v84, s20, v[68:69]
	ds_write_b128 v0, v[62:65]
	v_mul_u32_u24_e32 v0, 0x210, v163
	v_add3_u32 v170, s19, v164, v0
	v_mov_b32_e32 v48, 0
	v_mov_b32_e32 v49, v171
	v_mov_b32_e32 v50, v171
	v_mov_b32_e32 v51, v171
	v_mov_b32_e32 v52, v171
	v_mov_b32_e32 v53, v171
	v_mov_b32_e32 v54, v171
	v_mov_b32_e32 v55, v171
	v_mov_b32_e32 v56, v171
	v_mov_b32_e32 v57, v171
	v_mov_b32_e32 v58, v171
	v_mov_b32_e32 v59, v171
	v_mov_b32_e32 v60, v171
	v_mov_b32_e32 v61, v171
	v_mov_b32_e32 v62, v171
	v_mov_b32_e32 v63, v171
	v_mov_b32_e32 v33, v171
	v_mov_b32_e32 v34, v171
	v_mov_b32_e32 v35, v171
	v_mov_b32_e32 v36, v171
	v_mov_b32_e32 v37, v171
	v_mov_b32_e32 v38, v171
	v_mov_b32_e32 v39, v171
	v_mov_b32_e32 v40, v171
	v_mov_b32_e32 v41, v171
	v_mov_b32_e32 v42, v171
	v_mov_b32_e32 v43, v171
	v_mov_b32_e32 v44, v171
	v_mov_b32_e32 v45, v171
	v_mov_b32_e32 v46, v171
	v_mov_b32_e32 v47, v171
	v_mov_b32_e32 v16, 0
	v_mov_b32_e32 v17, v171
	v_mov_b32_e32 v18, v171
	v_mov_b32_e32 v19, v171
	v_mov_b32_e32 v20, v171
	v_mov_b32_e32 v21, v171
	v_mov_b32_e32 v22, v171
	v_mov_b32_e32 v23, v171
	v_mov_b32_e32 v24, v171
	v_mov_b32_e32 v25, v171
	v_mov_b32_e32 v26, v171
	v_mov_b32_e32 v27, v171
	v_mov_b32_e32 v28, v171
	v_mov_b32_e32 v29, v171
	v_mov_b32_e32 v30, v171
	v_mov_b32_e32 v31, v171
	v_mov_b32_e32 v0, 0
	v_mov_b32_e32 v1, v171
	v_mov_b32_e32 v2, v171
	v_mov_b32_e32 v3, v171
	v_mov_b32_e32 v4, v171
	v_mov_b32_e32 v5, v171
	v_mov_b32_e32 v6, v171
	v_mov_b32_e32 v7, v171
	v_mov_b32_e32 v8, v171
	v_mov_b32_e32 v9, v171
	v_mov_b32_e32 v10, v171
	v_mov_b32_e32 v11, v171
	v_mov_b32_e32 v12, v171
	v_mov_b32_e32 v13, v171
	v_mov_b32_e32 v14, v171
	v_mov_b32_e32 v15, v171
	s_waitcnt lgkmcnt(0)
	s_barrier
	s_cmp_eq_u64 s[6:7], 0
	s_cbranch_scc1 .LBB0_46
